# scores/softmax epilogue: row max / row sum butterfly steps via v_permlane16/32_swap instead of ds_bpermute (instruction selection, no LDS round trips)
# baseline (speedup 1.0000x reference)
.LBB0_1698:
	v_and_b32_e32 v136, 64, v233
	v_xor_b32_e32 v135, 16, v233
	v_add_u32_e32 v138, 64, v136
	v_cmp_lt_i32_e32 vcc, v135, v138
	s_mov_b32 s33, 0xff61b1e6
	s_nop 0
	v_cndmask_b32_e32 v135, v233, v135, vcc
	v_pk_mul_f32 v[200:201], v[126:127], v[134:135] op_sel_hi:[1,0]
	v_pk_mul_f32 v[176:177], v[122:123], v[134:135] op_sel_hi:[1,0]
	v_pk_mul_f32 v[204:205], v[124:125], v[134:135] op_sel_hi:[1,0]
	v_max_f32_e32 v124, v200, v201
	v_pk_mul_f32 v[120:121], v[120:121], v[134:135] op_sel_hi:[1,0]
	v_max_f32_e32 v122, v176, v177
	v_max3_f32 v124, v204, v205, v124
	v_max3_f32 v122, v120, v121, v122
	v_lshlrev_b32_e32 v241, 2, v135
	v_max3_f32 v135, v124, s33, v122
	v_pk_mul_f32 v[124:125], v[118:119], v[134:135] op_sel_hi:[1,0]
	v_pk_mul_f32 v[136:137], v[114:115], v[134:135] op_sel_hi:[1,0]
	v_pk_mul_f32 v[122:123], v[116:117], v[134:135] op_sel_hi:[1,0]
	v_max_f32_e32 v116, v124, v125
	v_pk_mul_f32 v[126:127], v[112:113], v[134:135] op_sel_hi:[1,0]
	v_max_f32_e32 v112, v136, v137
	v_max3_f32 v116, v122, v123, v116
	v_max3_f32 v112, v126, v127, v112
	v_max3_f32 v112, v135, v116, v112
	v_mov_b32_e32 v113, v112
	s_nop 1
	v_permlane16_swap_b32_e32 v112, v113
	v_xor_b32_e32 v114, 32, v233
	v_cmp_lt_i32_e32 vcc, v114, v138
	s_waitcnt lgkmcnt(0)
	v_max_f32_e32 v113, v113, v113
	v_cndmask_b32_e32 v114, v233, v114, vcc
	v_lshlrev_b32_e32 v242, 2, v114
	v_max_f32_e32 v112, v112, v113
	v_mov_b32_e32 v113, v112
	s_nop 1
	v_permlane32_swap_b32_e32 v112, v113
	v_add_u32_e32 v114, s26, v208
	s_and_saveexec_b64 s[0:1], s[6:7]
	s_cbranch_execz .LBB0_1700
	s_waitcnt lgkmcnt(0)
	v_max_f32_e32 v113, v113, v113
	v_max_f32_e32 v112, v112, v112
	v_max_f32_e32 v112, v112, v113
	ds_write_b32 v114, v112

.LBB0_1703:
	s_waitcnt lgkmcnt(0)
	v_pk_mul_f32 v[182:183], v[110:111], v[112:113] op_sel_hi:[1,0]
	v_pk_mul_f32 v[174:175], v[106:107], v[112:113] op_sel_hi:[1,0]
	v_pk_mul_f32 v[202:203], v[108:109], v[112:113] op_sel_hi:[1,0]
	v_max_f32_e32 v108, v182, v183
	v_pk_mul_f32 v[178:179], v[104:105], v[112:113] op_sel_hi:[1,0]
	v_max_f32_e32 v104, v174, v175
	v_pk_mul_f32 v[102:103], v[102:103], v[112:113] op_sel_hi:[1,0]
	v_pk_mul_f32 v[98:99], v[98:99], v[112:113] op_sel_hi:[1,0]
	v_max3_f32 v108, v202, v203, v108
	v_max3_f32 v104, v178, v179, v104
	v_pk_mul_f32 v[100:101], v[100:101], v[112:113] op_sel_hi:[1,0]
	v_max_f32_e32 v105, v102, v103
	v_pk_mul_f32 v[96:97], v[96:97], v[112:113] op_sel_hi:[1,0]
	v_max_f32_e32 v106, v98, v99
	v_max3_f32 v104, v108, s33, v104
	v_max3_f32 v105, v100, v101, v105
	v_max3_f32 v106, v96, v97, v106
	v_max3_f32 v104, v104, v105, v106
	v_mov_b32_e32 v105, v104
	s_nop 1
	v_permlane16_swap_b32_e32 v104, v105
	s_waitcnt lgkmcnt(0)
	v_max_f32_e32 v105, v105, v105
	v_max_f32_e32 v104, v104, v105
	v_mov_b32_e32 v105, v104
	s_nop 1
	v_permlane32_swap_b32_e32 v104, v105
	s_and_saveexec_b64 s[0:1], s[6:7]
	s_cbranch_execz .LBB0_1705
	s_waitcnt lgkmcnt(0)
	v_max_f32_e32 v105, v105, v105
	v_max_f32_e32 v104, v104, v104
	v_max_f32_e32 v104, v104, v105
	ds_write_b32 v114, v104 offset:256

.LBB0_1708:
	v_pk_mul_f32 v[172:173], v[94:95], v[110:111] op_sel_hi:[1,0]
	s_waitcnt lgkmcnt(0)
	v_pk_mul_f32 v[104:105], v[90:91], v[110:111] op_sel_hi:[1,0]
	v_pk_mul_f32 v[180:181], v[92:93], v[110:111] op_sel_hi:[1,0]
	v_max_f32_e32 v92, v172, v173
	v_pk_mul_f32 v[168:169], v[88:89], v[110:111] op_sel_hi:[1,0]
	v_max_f32_e32 v88, v104, v105
	v_pk_mul_f32 v[108:109], v[86:87], v[110:111] op_sel_hi:[1,0]
	v_pk_mul_f32 v[112:113], v[82:83], v[110:111] op_sel_hi:[1,0]
	v_max3_f32 v92, v180, v181, v92
	v_max3_f32 v88, v168, v169, v88
	v_pk_mul_f32 v[106:107], v[84:85], v[110:111] op_sel_hi:[1,0]
	v_max_f32_e32 v84, v108, v109
	v_pk_mul_f32 v[110:111], v[80:81], v[110:111] op_sel_hi:[1,0]
	v_max_f32_e32 v80, v112, v113
	v_max3_f32 v88, v92, s33, v88
	v_max3_f32 v84, v106, v107, v84
	v_max3_f32 v80, v110, v111, v80
	v_max3_f32 v80, v88, v84, v80
	v_mov_b32_e32 v81, v80
	s_nop 1
	v_permlane16_swap_b32_e32 v80, v81
	s_waitcnt lgkmcnt(0)
	v_max_f32_e32 v81, v81, v81
	v_max_f32_e32 v80, v80, v81
	v_mov_b32_e32 v81, v80
	s_nop 1
	v_permlane32_swap_b32_e32 v80, v81
	s_and_saveexec_b64 s[0:1], s[6:7]
	s_cbranch_execz .LBB0_1710
	s_waitcnt lgkmcnt(0)
	v_max_f32_e32 v81, v81, v81
	v_max_f32_e32 v80, v80, v80
	v_max_f32_e32 v80, v80, v81
	ds_write_b32 v114, v80 offset:512

.LBB0_1713:
	s_waitcnt lgkmcnt(0)
	v_pk_mul_f32 v[166:167], v[78:79], v[80:81] op_sel_hi:[1,0]
	v_pk_mul_f32 v[160:161], v[74:75], v[80:81] op_sel_hi:[1,0]
	v_pk_mul_f32 v[170:171], v[76:77], v[80:81] op_sel_hi:[1,0]
	v_max_f32_e32 v76, v166, v167
	v_pk_mul_f32 v[162:163], v[72:73], v[80:81] op_sel_hi:[1,0]
	v_max_f32_e32 v72, v160, v161
	v_pk_mul_f32 v[70:71], v[70:71], v[80:81] op_sel_hi:[1,0]
	v_pk_mul_f32 v[66:67], v[66:67], v[80:81] op_sel_hi:[1,0]
	v_max3_f32 v76, v170, v171, v76
	v_max3_f32 v72, v162, v163, v72
	v_pk_mul_f32 v[68:69], v[68:69], v[80:81] op_sel_hi:[1,0]
	v_max_f32_e32 v73, v70, v71
	v_pk_mul_f32 v[64:65], v[64:65], v[80:81] op_sel_hi:[1,0]
	v_max_f32_e32 v74, v66, v67
	v_max3_f32 v72, v76, s33, v72
	v_max3_f32 v73, v68, v69, v73
	v_max3_f32 v74, v64, v65, v74
	v_max3_f32 v72, v72, v73, v74
	v_mov_b32_e32 v73, v72
	s_nop 1
	v_permlane16_swap_b32_e32 v72, v73
	s_waitcnt lgkmcnt(0)
	v_max_f32_e32 v73, v73, v73
	v_max_f32_e32 v72, v72, v73
	v_mov_b32_e32 v73, v72
	s_nop 1
	v_permlane32_swap_b32_e32 v72, v73
	s_and_saveexec_b64 s[0:1], s[6:7]
	s_cbranch_execz .LBB0_1715
	s_waitcnt lgkmcnt(0)
	v_max_f32_e32 v73, v73, v73
	v_max_f32_e32 v72, v72, v72
	v_max_f32_e32 v72, v72, v73
	ds_write_b32 v114, v72 offset:768

.LBB0_1718:
	v_pk_mul_f32 v[158:159], v[62:63], v[78:79] op_sel_hi:[1,0]
	s_waitcnt lgkmcnt(0)
	v_pk_mul_f32 v[72:73], v[58:59], v[78:79] op_sel_hi:[1,0]
	v_pk_mul_f32 v[164:165], v[60:61], v[78:79] op_sel_hi:[1,0]
	v_max_f32_e32 v60, v158, v159
	v_pk_mul_f32 v[154:155], v[56:57], v[78:79] op_sel_hi:[1,0]
	v_max_f32_e32 v56, v72, v73
	v_pk_mul_f32 v[76:77], v[54:55], v[78:79] op_sel_hi:[1,0]
	v_pk_mul_f32 v[80:81], v[50:51], v[78:79] op_sel_hi:[1,0]
	v_max3_f32 v60, v164, v165, v60
	v_max3_f32 v56, v154, v155, v56
	v_pk_mul_f32 v[74:75], v[52:53], v[78:79] op_sel_hi:[1,0]
	v_max_f32_e32 v52, v76, v77
	v_pk_mul_f32 v[78:79], v[48:49], v[78:79] op_sel_hi:[1,0]
	v_max_f32_e32 v48, v80, v81
	v_max3_f32 v56, v60, s33, v56
	v_max3_f32 v52, v74, v75, v52
	v_max3_f32 v48, v78, v79, v48
	v_max3_f32 v48, v56, v52, v48
	v_mov_b32_e32 v49, v48
	s_nop 1
	v_permlane16_swap_b32_e32 v48, v49
	s_waitcnt lgkmcnt(0)
	v_max_f32_e32 v49, v49, v49
	v_max_f32_e32 v48, v48, v49
	v_mov_b32_e32 v49, v48
	s_nop 1
	v_permlane32_swap_b32_e32 v48, v49
	s_and_saveexec_b64 s[0:1], s[6:7]
	s_cbranch_execz .LBB0_1720
	s_waitcnt lgkmcnt(0)
	v_max_f32_e32 v49, v49, v49
	v_max_f32_e32 v48, v48, v48
	v_max_f32_e32 v48, v48, v49
	ds_write_b32 v114, v48 offset:2048

.LBB0_1723:
	s_waitcnt lgkmcnt(0)
	v_pk_mul_f32 v[152:153], v[46:47], v[48:49] op_sel_hi:[1,0]
	v_pk_mul_f32 v[146:147], v[42:43], v[48:49] op_sel_hi:[1,0]
	v_pk_mul_f32 v[156:157], v[44:45], v[48:49] op_sel_hi:[1,0]
	v_max_f32_e32 v44, v152, v153
	v_pk_mul_f32 v[148:149], v[40:41], v[48:49] op_sel_hi:[1,0]
	v_max_f32_e32 v40, v146, v147
	v_pk_mul_f32 v[38:39], v[38:39], v[48:49] op_sel_hi:[1,0]
	v_pk_mul_f32 v[34:35], v[34:35], v[48:49] op_sel_hi:[1,0]
	v_max3_f32 v44, v156, v157, v44
	v_max3_f32 v40, v148, v149, v40
	v_pk_mul_f32 v[36:37], v[36:37], v[48:49] op_sel_hi:[1,0]
	v_max_f32_e32 v41, v38, v39
	v_pk_mul_f32 v[32:33], v[32:33], v[48:49] op_sel_hi:[1,0]
	v_max_f32_e32 v42, v34, v35
	v_max3_f32 v40, v44, s33, v40
	v_max3_f32 v41, v36, v37, v41
	v_max3_f32 v42, v32, v33, v42
	v_max3_f32 v40, v40, v41, v42
	v_mov_b32_e32 v41, v40
	s_nop 1
	v_permlane16_swap_b32_e32 v40, v41
	s_waitcnt lgkmcnt(0)
	v_max_f32_e32 v41, v41, v41
	v_max_f32_e32 v40, v40, v41
	v_mov_b32_e32 v41, v40
	s_nop 1
	v_permlane32_swap_b32_e32 v40, v41
	s_and_saveexec_b64 s[0:1], s[6:7]
	s_cbranch_execz .LBB0_1725
	s_waitcnt lgkmcnt(0)
	v_max_f32_e32 v41, v41, v41
	v_max_f32_e32 v40, v40, v40
	v_max_f32_e32 v40, v40, v41
	ds_write_b32 v114, v40 offset:2304

.LBB0_1728:
	v_pk_mul_f32 v[144:145], v[30:31], v[50:51] op_sel_hi:[1,0]
	s_waitcnt lgkmcnt(0)
	v_pk_mul_f32 v[40:41], v[26:27], v[50:51] op_sel_hi:[1,0]
	v_pk_mul_f32 v[150:151], v[28:29], v[50:51] op_sel_hi:[1,0]
	v_max_f32_e32 v28, v144, v145
	v_pk_mul_f32 v[46:47], v[24:25], v[50:51] op_sel_hi:[1,0]
	v_max_f32_e32 v24, v40, v41
	v_pk_mul_f32 v[44:45], v[22:23], v[50:51] op_sel_hi:[1,0]
	v_pk_mul_f32 v[48:49], v[18:19], v[50:51] op_sel_hi:[1,0]
	v_max3_f32 v28, v150, v151, v28
	v_max3_f32 v24, v46, v47, v24
	v_pk_mul_f32 v[42:43], v[20:21], v[50:51] op_sel_hi:[1,0]
	v_max_f32_e32 v20, v44, v45
	v_pk_mul_f32 v[16:17], v[16:17], v[50:51] op_sel_hi:[1,0]
	v_max_f32_e32 v18, v48, v49
	v_max3_f32 v24, v28, s33, v24
	v_max3_f32 v20, v42, v43, v20
	v_max3_f32 v18, v16, v17, v18
	v_max3_f32 v18, v24, v20, v18
	v_mov_b32_e32 v19, v18
	s_nop 1
	v_permlane16_swap_b32_e32 v18, v19
	s_waitcnt lgkmcnt(0)
	v_max_f32_e32 v19, v19, v19
	v_max_f32_e32 v18, v18, v19
	v_mov_b32_e32 v19, v18
	s_nop 1
	v_permlane32_swap_b32_e32 v18, v19
	s_and_saveexec_b64 s[0:1], s[6:7]
	s_cbranch_execz .LBB0_1730
	s_waitcnt lgkmcnt(0)
	v_max_f32_e32 v19, v19, v19
	v_max_f32_e32 v18, v18, v18
	v_max_f32_e32 v18, v18, v19
	ds_write_b32 v114, v18 offset:2560

.LBB0_1733:
	s_waitcnt lgkmcnt(0)
	v_pk_mul_f32 v[140:141], v[14:15], v[18:19] op_sel_hi:[1,0]
	v_pk_mul_f32 v[142:143], v[12:13], v[18:19] op_sel_hi:[1,0]
	v_max_f32_e32 v12, v140, v141
	v_max3_f32 v14, v142, v143, v12
	v_pk_mul_f32 v[12:13], v[10:11], v[18:19] op_sel_hi:[1,0]
	v_pk_mul_f32 v[138:139], v[8:9], v[18:19] op_sel_hi:[1,0]
	v_max_f32_e32 v8, v12, v13
	v_max3_f32 v8, v138, v139, v8
	v_max3_f32 v19, v14, s33, v8
	v_pk_mul_f32 v[8:9], v[6:7], v[18:19] op_sel_hi:[1,0]
	v_pk_mul_f32 v[14:15], v[2:3], v[18:19] op_sel_hi:[1,0]
	v_pk_mul_f32 v[134:135], v[4:5], v[18:19] op_sel_hi:[1,0]
	v_max_f32_e32 v4, v8, v9
	v_pk_mul_f32 v[10:11], v[0:1], v[18:19] op_sel_hi:[1,0]
	v_max_f32_e32 v0, v14, v15
	v_max3_f32 v4, v134, v135, v4
	v_max3_f32 v0, v10, v11, v0
	v_max3_f32 v0, v19, v4, v0
	v_mov_b32_e32 v1, v0
	s_nop 1
	v_permlane16_swap_b32_e32 v0, v1
	s_waitcnt lgkmcnt(0)
	v_max_f32_e32 v1, v1, v1
	v_max_f32_e32 v0, v0, v1
	v_mov_b32_e32 v1, v0
	s_nop 1
	v_permlane32_swap_b32_e32 v0, v1
	s_and_saveexec_b64 s[0:1], s[6:7]
	s_cbranch_execz .LBB0_1735
	s_waitcnt lgkmcnt(0)
	v_max_f32_e32 v1, v1, v1
	v_max_f32_e32 v0, v0, v0
	v_max_f32_e32 v0, v0, v1
	ds_write_b32 v114, v0 offset:2816
.LBB0_1735:
	s_or_b64 exec, exec, s[0:1]
	s_waitcnt lgkmcnt(0)
	s_barrier
	s_waitcnt lgkmcnt(0)
	ds_read_b128 v[0:3], v209
	s_waitcnt lgkmcnt(0)
	v_max_f32_e32 v3, v3, v3
	v_max_f32_e32 v2, v2, v2
	v_max_f32_e32 v2, v2, v3
	v_max3_f32 v0, v0, v1, v2
	v_sub_f32_e32 v1, v204, v0
	v_sub_f32_e32 v3, v120, v0
	v_exp_f32_e32 v114, v1
	v_sub_f32_e32 v1, v200, v0
	v_exp_f32_e32 v118, v3
	v_sub_f32_e32 v3, v121, v0
	v_sub_f32_e32 v4, v122, v0
	v_sub_f32_e32 v2, v205, v0
	v_exp_f32_e32 v116, v1
	v_sub_f32_e32 v1, v201, v0
	v_exp_f32_e32 v119, v3
	v_sub_f32_e32 v3, v176, v0
	v_exp_f32_e32 v122, v4
	v_sub_f32_e32 v4, v123, v0
	v_exp_f32_e32 v115, v2
	v_exp_f32_e32 v117, v1
	v_exp_f32_e32 v120, v3
	v_sub_f32_e32 v3, v177, v0
	v_exp_f32_e32 v123, v4
	v_sub_f32_e32 v4, v124, v0
	v_exp_f32_e32 v121, v3
	v_exp_f32_e32 v124, v4
	v_sub_f32_e32 v4, v125, v0
	v_exp_f32_e32 v125, v4
	v_sub_f32_e32 v4, v126, v0
	v_exp_f32_e32 v126, v4
	v_sub_f32_e32 v4, v127, v0
	v_add_f32_e32 v1, v114, v115
	v_add_f32_e32 v2, v116, v117
	v_exp_f32_e32 v127, v4
	v_sub_f32_e32 v4, v136, v0
	v_sub_f32_e32 v0, v137, v0
	v_add_f32_e32 v1, v1, v2
	v_add_f32_e32 v2, v118, v119
	v_add_f32_e32 v3, v120, v121
	v_exp_f32_e32 v136, v4
	v_exp_f32_e32 v137, v0
	v_add_f32_e32 v1, 0, v1
	v_add_f32_e32 v2, v2, v3
	v_add_f32_e32 v1, v2, v1
	v_add_f32_e32 v2, v122, v123
	v_add_f32_e32 v3, v124, v125
	v_add_f32_e32 v0, v2, v3
	v_add_f32_e32 v0, v0, v1
	v_add_f32_e32 v1, v126, v127
	v_add_f32_e32 v2, v136, v137
	v_add_f32_e32 v1, v1, v2
	v_add_f32_e32 v0, v1, v0
	v_mov_b32_e32 v1, v0
	s_nop 1
	v_permlane16_swap_b32_e32 v0, v1
	s_waitcnt lgkmcnt(0)
	v_add_f32_e32 v0, v0, v1
	v_mov_b32_e32 v1, v0
	s_nop 1
	v_permlane32_swap_b32_e32 v0, v1
	s_and_saveexec_b64 s[0:1], s[6:7]
	s_cbranch_execz .LBB0_1737
	s_waitcnt lgkmcnt(0)
	v_add_f32_e32 v0, v0, v1
	ds_write_b32 v210, v0
.LBB0_1737:
	s_or_b64 exec, exec, s[0:1]
	s_waitcnt lgkmcnt(0)
	ds_read_b128 v[0:3], v211
	s_waitcnt lgkmcnt(0)
	v_max_f32_e32 v3, v3, v3
	v_max_f32_e32 v2, v2, v2
	v_max_f32_e32 v2, v2, v3
	v_max3_f32 v0, v0, v1, v2
	v_sub_f32_e32 v3, v182, v0
	v_exp_f32_e32 v88, v3
	v_sub_f32_e32 v3, v178, v0
	v_sub_f32_e32 v1, v202, v0
	v_exp_f32_e32 v86, v3
	v_sub_f32_e32 v3, v179, v0
	v_sub_f32_e32 v4, v100, v0
	v_sub_f32_e32 v2, v203, v0
	v_exp_f32_e32 v82, v1
	v_sub_f32_e32 v1, v183, v0
	v_exp_f32_e32 v87, v3
	v_sub_f32_e32 v3, v174, v0
	v_exp_f32_e32 v84, v4
	v_sub_f32_e32 v4, v101, v0
	v_exp_f32_e32 v83, v2
	v_exp_f32_e32 v89, v1
	v_exp_f32_e32 v94, v3
	v_sub_f32_e32 v3, v175, v0
	v_exp_f32_e32 v85, v4
	v_sub_f32_e32 v4, v102, v0
	v_exp_f32_e32 v95, v3
	v_exp_f32_e32 v90, v4
	v_sub_f32_e32 v4, v103, v0
	v_exp_f32_e32 v91, v4
	v_sub_f32_e32 v4, v96, v0
	v_exp_f32_e32 v92, v4
	v_sub_f32_e32 v4, v97, v0
	v_add_f32_e32 v1, v82, v83
	v_add_f32_e32 v2, v88, v89
	v_exp_f32_e32 v93, v4
	v_sub_f32_e32 v4, v98, v0
	v_sub_f32_e32 v0, v99, v0
	v_add_f32_e32 v1, v1, v2
	v_add_f32_e32 v2, v86, v87
	v_add_f32_e32 v3, v94, v95
	v_exp_f32_e32 v100, v4
	v_exp_f32_e32 v101, v0
	v_add_f32_e32 v1, 0, v1
	v_add_f32_e32 v2, v2, v3
	v_add_f32_e32 v1, v2, v1
	v_add_f32_e32 v2, v84, v85
	v_add_f32_e32 v3, v90, v91
	v_add_f32_e32 v0, v2, v3
	v_add_f32_e32 v0, v0, v1
	v_add_f32_e32 v1, v92, v93
	v_add_f32_e32 v2, v100, v101
	v_add_f32_e32 v1, v1, v2
	v_add_f32_e32 v0, v1, v0
	v_mov_b32_e32 v1, v0
	s_nop 1
	v_permlane16_swap_b32_e32 v0, v1
	s_waitcnt lgkmcnt(0)
	v_add_f32_e32 v0, v0, v1
	v_mov_b32_e32 v1, v0
	s_nop 1
	v_permlane32_swap_b32_e32 v0, v1
	s_and_saveexec_b64 s[0:1], s[6:7]
	s_cbranch_execz .LBB0_1739
	s_waitcnt lgkmcnt(0)
	v_add_f32_e32 v0, v0, v1
	ds_write_b32 v210, v0 offset:256
.LBB0_1739:
	s_or_b64 exec, exec, s[0:1]
	s_waitcnt lgkmcnt(0)
	ds_read_b128 v[0:3], v212
	s_waitcnt lgkmcnt(0)
	v_max_f32_e32 v3, v3, v3
	v_max_f32_e32 v2, v2, v2
	v_max_f32_e32 v2, v2, v3
	v_max3_f32 v0, v0, v1, v2
	v_sub_f32_e32 v3, v172, v0
	v_exp_f32_e32 v98, v3
	v_sub_f32_e32 v3, v168, v0
	v_sub_f32_e32 v1, v180, v0
	v_exp_f32_e32 v102, v3
	v_sub_f32_e32 v3, v169, v0
	v_sub_f32_e32 v4, v106, v0
	v_sub_f32_e32 v2, v181, v0
	v_exp_f32_e32 v96, v1
	v_sub_f32_e32 v1, v173, v0
	v_exp_f32_e32 v103, v3
	v_sub_f32_e32 v3, v104, v0
	v_exp_f32_e32 v106, v4
	v_sub_f32_e32 v4, v107, v0
	v_exp_f32_e32 v97, v2
	v_exp_f32_e32 v99, v1
	v_exp_f32_e32 v104, v3
	v_sub_f32_e32 v3, v105, v0
	v_exp_f32_e32 v107, v4
	v_sub_f32_e32 v4, v108, v0
	v_exp_f32_e32 v105, v3
	v_exp_f32_e32 v108, v4
	v_sub_f32_e32 v4, v109, v0
	v_exp_f32_e32 v109, v4
	v_sub_f32_e32 v4, v110, v0
	v_exp_f32_e32 v110, v4
	v_sub_f32_e32 v4, v111, v0
	v_add_f32_e32 v1, v96, v97
	v_add_f32_e32 v2, v98, v99
	v_exp_f32_e32 v111, v4
	v_sub_f32_e32 v4, v112, v0
	v_sub_f32_e32 v0, v113, v0
	v_add_f32_e32 v1, v1, v2
	v_add_f32_e32 v2, v102, v103
	v_add_f32_e32 v3, v104, v105
	v_exp_f32_e32 v112, v4
	v_exp_f32_e32 v113, v0
	v_add_f32_e32 v1, 0, v1
	v_add_f32_e32 v2, v2, v3
	v_add_f32_e32 v1, v2, v1
	v_add_f32_e32 v2, v106, v107
	v_add_f32_e32 v3, v108, v109
	v_add_f32_e32 v0, v2, v3
	v_add_f32_e32 v0, v0, v1
	v_add_f32_e32 v1, v110, v111
	v_add_f32_e32 v2, v112, v113
	v_add_f32_e32 v1, v1, v2
	v_add_f32_e32 v0, v1, v0
	v_mov_b32_e32 v1, v0
	s_nop 1
	v_permlane16_swap_b32_e32 v0, v1
	s_waitcnt lgkmcnt(0)
	v_add_f32_e32 v0, v0, v1
	v_mov_b32_e32 v1, v0
	s_nop 1
	v_permlane32_swap_b32_e32 v0, v1
	s_and_saveexec_b64 s[0:1], s[6:7]
	s_cbranch_execz .LBB0_1741
	s_waitcnt lgkmcnt(0)
	v_add_f32_e32 v0, v0, v1
	ds_write_b32 v210, v0 offset:512
.LBB0_1741:
	s_or_b64 exec, exec, s[0:1]
	s_waitcnt lgkmcnt(0)
	ds_read_b128 v[0:3], v213
	s_waitcnt lgkmcnt(0)
	v_max_f32_e32 v3, v3, v3
	v_max_f32_e32 v2, v2, v2
	v_max_f32_e32 v2, v2, v3
	v_max3_f32 v0, v0, v1, v2
	v_sub_f32_e32 v3, v166, v0
	v_exp_f32_e32 v56, v3
	v_sub_f32_e32 v3, v162, v0
	v_sub_f32_e32 v1, v170, v0
	v_exp_f32_e32 v54, v3
	v_sub_f32_e32 v3, v163, v0
	v_sub_f32_e32 v4, v68, v0
	v_sub_f32_e32 v2, v171, v0
	v_exp_f32_e32 v50, v1
	v_sub_f32_e32 v1, v167, v0
	v_exp_f32_e32 v55, v3
	v_sub_f32_e32 v3, v160, v0
	v_exp_f32_e32 v52, v4
	v_sub_f32_e32 v4, v69, v0
	v_exp_f32_e32 v51, v2
	v_exp_f32_e32 v57, v1
	v_exp_f32_e32 v62, v3
	v_sub_f32_e32 v3, v161, v0
	v_exp_f32_e32 v53, v4
	v_sub_f32_e32 v4, v70, v0
	v_exp_f32_e32 v63, v3
	v_exp_f32_e32 v58, v4
	v_sub_f32_e32 v4, v71, v0
	v_exp_f32_e32 v59, v4
	v_sub_f32_e32 v4, v64, v0
	v_exp_f32_e32 v60, v4
	v_sub_f32_e32 v4, v65, v0
	v_add_f32_e32 v1, v50, v51
	v_add_f32_e32 v2, v56, v57
	v_exp_f32_e32 v61, v4
	v_sub_f32_e32 v4, v66, v0
	v_sub_f32_e32 v0, v67, v0
	v_add_f32_e32 v1, v1, v2
	v_add_f32_e32 v2, v54, v55
	v_add_f32_e32 v3, v62, v63
	v_exp_f32_e32 v68, v4
	v_exp_f32_e32 v69, v0
	v_add_f32_e32 v1, 0, v1
	v_add_f32_e32 v2, v2, v3
	v_add_f32_e32 v1, v2, v1
	v_add_f32_e32 v2, v52, v53
	v_add_f32_e32 v3, v58, v59
	v_add_f32_e32 v0, v2, v3
	v_add_f32_e32 v0, v0, v1
	v_add_f32_e32 v1, v60, v61
	v_add_f32_e32 v2, v68, v69
	v_add_f32_e32 v1, v1, v2
	v_add_f32_e32 v0, v1, v0
	v_mov_b32_e32 v1, v0
	s_nop 1
	v_permlane16_swap_b32_e32 v0, v1
	s_waitcnt lgkmcnt(0)
	v_add_f32_e32 v0, v0, v1
	v_mov_b32_e32 v1, v0
	s_nop 1
	v_permlane32_swap_b32_e32 v0, v1
	s_and_saveexec_b64 s[0:1], s[6:7]
	s_cbranch_execz .LBB0_1743
	s_waitcnt lgkmcnt(0)
	v_add_f32_e32 v0, v0, v1
	ds_write_b32 v210, v0 offset:768
.LBB0_1743:
	s_or_b64 exec, exec, s[0:1]
	s_waitcnt lgkmcnt(0)
	ds_read_b128 v[0:3], v214
	s_waitcnt lgkmcnt(0)
	v_max_f32_e32 v3, v3, v3
	v_max_f32_e32 v2, v2, v2
	v_max_f32_e32 v2, v2, v3
	v_max3_f32 v0, v0, v1, v2
	v_sub_f32_e32 v3, v158, v0
	v_exp_f32_e32 v66, v3
	v_sub_f32_e32 v3, v154, v0
	v_sub_f32_e32 v1, v164, v0
	v_exp_f32_e32 v70, v3
	v_sub_f32_e32 v3, v155, v0
	v_sub_f32_e32 v4, v74, v0
	v_sub_f32_e32 v2, v165, v0
	v_exp_f32_e32 v64, v1
	v_sub_f32_e32 v1, v159, v0
	v_exp_f32_e32 v71, v3
	v_sub_f32_e32 v3, v72, v0
	v_exp_f32_e32 v74, v4
	v_sub_f32_e32 v4, v75, v0
	v_exp_f32_e32 v65, v2
	v_exp_f32_e32 v67, v1
	v_exp_f32_e32 v72, v3
	v_sub_f32_e32 v3, v73, v0
	v_exp_f32_e32 v75, v4
	v_sub_f32_e32 v4, v76, v0
	v_exp_f32_e32 v73, v3
	v_exp_f32_e32 v76, v4
	v_sub_f32_e32 v4, v77, v0
	v_exp_f32_e32 v77, v4
	v_sub_f32_e32 v4, v78, v0
	v_exp_f32_e32 v78, v4
	v_sub_f32_e32 v4, v79, v0
	v_add_f32_e32 v1, v64, v65
	v_add_f32_e32 v2, v66, v67
	v_exp_f32_e32 v79, v4
	v_sub_f32_e32 v4, v80, v0
	v_sub_f32_e32 v0, v81, v0
	v_add_f32_e32 v1, v1, v2
	v_add_f32_e32 v2, v70, v71
	v_add_f32_e32 v3, v72, v73
	v_exp_f32_e32 v80, v4
	v_exp_f32_e32 v81, v0
	v_add_f32_e32 v1, 0, v1
	v_add_f32_e32 v2, v2, v3
	v_add_f32_e32 v1, v2, v1
	v_add_f32_e32 v2, v74, v75
	v_add_f32_e32 v3, v76, v77
	v_add_f32_e32 v0, v2, v3
	v_add_f32_e32 v0, v0, v1
	v_add_f32_e32 v1, v78, v79
	v_add_f32_e32 v2, v80, v81
	v_add_f32_e32 v1, v1, v2
	v_add_f32_e32 v0, v1, v0
	v_mov_b32_e32 v1, v0
	s_nop 1
	v_permlane16_swap_b32_e32 v0, v1
	s_waitcnt lgkmcnt(0)
	v_add_f32_e32 v0, v0, v1
	v_mov_b32_e32 v1, v0
	s_nop 1
	v_permlane32_swap_b32_e32 v0, v1
	s_and_saveexec_b64 s[0:1], s[6:7]
	s_cbranch_execz .LBB0_1745
	s_waitcnt lgkmcnt(0)
	v_add_f32_e32 v0, v0, v1
	ds_write_b32 v210, v0 offset:2048
.LBB0_1745:
	s_or_b64 exec, exec, s[0:1]
	s_waitcnt lgkmcnt(0)
	ds_read_b128 v[0:3], v215
	s_waitcnt lgkmcnt(0)
	v_max_f32_e32 v3, v3, v3
	v_max_f32_e32 v2, v2, v2
	v_max_f32_e32 v2, v2, v3
	v_max3_f32 v0, v0, v1, v2
	v_sub_f32_e32 v3, v152, v0
	v_exp_f32_e32 v24, v3
	v_sub_f32_e32 v3, v148, v0
	v_sub_f32_e32 v1, v156, v0
	v_exp_f32_e32 v22, v3
	v_sub_f32_e32 v3, v149, v0
	v_sub_f32_e32 v4, v36, v0
	v_sub_f32_e32 v2, v157, v0
	v_exp_f32_e32 v18, v1
	v_sub_f32_e32 v1, v153, v0
	v_exp_f32_e32 v23, v3
	v_sub_f32_e32 v3, v146, v0
	v_exp_f32_e32 v20, v4
	v_sub_f32_e32 v4, v37, v0
	v_exp_f32_e32 v19, v2
	v_exp_f32_e32 v25, v1
	v_exp_f32_e32 v30, v3
	v_sub_f32_e32 v3, v147, v0
	v_exp_f32_e32 v21, v4
	v_sub_f32_e32 v4, v38, v0
	v_exp_f32_e32 v31, v3
	v_exp_f32_e32 v26, v4
	v_sub_f32_e32 v4, v39, v0
	v_exp_f32_e32 v27, v4
	v_sub_f32_e32 v4, v32, v0
	v_exp_f32_e32 v28, v4
	v_sub_f32_e32 v4, v33, v0
	v_add_f32_e32 v1, v18, v19
	v_add_f32_e32 v2, v24, v25
	v_exp_f32_e32 v29, v4
	v_sub_f32_e32 v4, v34, v0
	v_sub_f32_e32 v0, v35, v0
	v_add_f32_e32 v1, v1, v2
	v_add_f32_e32 v2, v22, v23
	v_add_f32_e32 v3, v30, v31
	v_exp_f32_e32 v36, v4
	v_exp_f32_e32 v37, v0
	v_add_f32_e32 v1, 0, v1
	v_add_f32_e32 v2, v2, v3
	v_add_f32_e32 v1, v2, v1
	v_add_f32_e32 v2, v20, v21
	v_add_f32_e32 v3, v26, v27
	v_add_f32_e32 v0, v2, v3
	v_add_f32_e32 v0, v0, v1
	v_add_f32_e32 v1, v28, v29
	v_add_f32_e32 v2, v36, v37
	v_add_f32_e32 v1, v1, v2
	v_add_f32_e32 v0, v1, v0
	v_mov_b32_e32 v1, v0
	s_nop 1
	v_permlane16_swap_b32_e32 v0, v1
	s_waitcnt lgkmcnt(0)
	v_add_f32_e32 v0, v0, v1
	v_mov_b32_e32 v1, v0
	s_nop 1
	v_permlane32_swap_b32_e32 v0, v1
	s_and_saveexec_b64 s[0:1], s[6:7]
	s_cbranch_execz .LBB0_1747
	s_waitcnt lgkmcnt(0)
	v_add_f32_e32 v0, v0, v1
	ds_write_b32 v210, v0 offset:2304
.LBB0_1747:
	s_or_b64 exec, exec, s[0:1]
	s_waitcnt lgkmcnt(0)
	ds_read_b128 v[0:3], v216
	s_waitcnt lgkmcnt(0)
	v_max_f32_e32 v3, v3, v3
	v_max_f32_e32 v2, v2, v2
	v_max_f32_e32 v2, v2, v3
	v_max3_f32 v0, v0, v1, v2
	v_sub_f32_e32 v3, v144, v0
	v_exp_f32_e32 v34, v3
	v_sub_f32_e32 v3, v46, v0
	v_sub_f32_e32 v1, v150, v0
	v_exp_f32_e32 v38, v3
	v_sub_f32_e32 v3, v47, v0
	v_sub_f32_e32 v4, v42, v0
	v_sub_f32_e32 v2, v151, v0
	v_exp_f32_e32 v32, v1
	v_sub_f32_e32 v1, v145, v0
	v_exp_f32_e32 v39, v3
	v_sub_f32_e32 v3, v40, v0
	v_exp_f32_e32 v42, v4
	v_sub_f32_e32 v4, v43, v0
	v_exp_f32_e32 v33, v2
	v_exp_f32_e32 v35, v1
	v_exp_f32_e32 v40, v3
	v_sub_f32_e32 v3, v41, v0
	v_exp_f32_e32 v43, v4
	v_sub_f32_e32 v4, v44, v0
	v_exp_f32_e32 v41, v3
	v_exp_f32_e32 v44, v4
	v_sub_f32_e32 v4, v45, v0
	v_exp_f32_e32 v45, v4
	v_sub_f32_e32 v4, v16, v0
	v_exp_f32_e32 v46, v4
	v_sub_f32_e32 v4, v17, v0
	v_add_f32_e32 v1, v32, v33
	v_add_f32_e32 v2, v34, v35
	v_exp_f32_e32 v47, v4
	v_sub_f32_e32 v4, v48, v0
	v_sub_f32_e32 v0, v49, v0
	v_add_f32_e32 v1, v1, v2
	v_add_f32_e32 v2, v38, v39
	v_add_f32_e32 v3, v40, v41
	v_exp_f32_e32 v48, v4
	v_exp_f32_e32 v49, v0
	v_add_f32_e32 v1, 0, v1
	v_add_f32_e32 v2, v2, v3
	v_add_f32_e32 v1, v2, v1
	v_add_f32_e32 v2, v42, v43
	v_add_f32_e32 v3, v44, v45
	v_add_f32_e32 v0, v2, v3
	v_add_f32_e32 v0, v0, v1
	v_add_f32_e32 v1, v46, v47
	v_add_f32_e32 v2, v48, v49
	v_add_f32_e32 v1, v1, v2
	v_add_f32_e32 v0, v1, v0
	v_mov_b32_e32 v1, v0
	s_nop 1
	v_permlane16_swap_b32_e32 v0, v1
	s_waitcnt lgkmcnt(0)
	v_add_f32_e32 v0, v0, v1
	v_mov_b32_e32 v1, v0
	s_nop 1
	v_permlane32_swap_b32_e32 v0, v1
	s_and_saveexec_b64 s[0:1], s[6:7]
	s_cbranch_execz .LBB0_1749
	s_waitcnt lgkmcnt(0)
	v_add_f32_e32 v0, v0, v1
	ds_write_b32 v210, v0 offset:2560
.LBB0_1749:
	s_or_b64 exec, exec, s[0:1]
	s_waitcnt lgkmcnt(0)
	ds_read_b128 v[0:3], v217
	s_waitcnt lgkmcnt(0)
	v_max_f32_e32 v3, v3, v3
	v_max_f32_e32 v2, v2, v2
	v_max_f32_e32 v2, v2, v3
	v_max3_f32 v16, v0, v1, v2
	v_sub_f32_e32 v2, v140, v16
	v_sub_f32_e32 v0, v142, v16
	v_sub_f32_e32 v1, v143, v16
	v_exp_f32_e32 v6, v2
	v_sub_f32_e32 v2, v141, v16
	v_exp_f32_e32 v0, v0
	v_exp_f32_e32 v1, v1
	v_exp_f32_e32 v7, v2
	v_sub_f32_e32 v4, v138, v16
	v_sub_f32_e32 v5, v139, v16
	v_add_f32_e32 v2, v0, v1
	v_add_f32_e32 v3, v6, v7
	v_sub_f32_e32 v12, v12, v16
	v_sub_f32_e32 v13, v13, v16
	v_exp_f32_e32 v4, v4
	v_exp_f32_e32 v5, v5
	v_exp_f32_e32 v12, v12
	v_exp_f32_e32 v13, v13
	v_add_f32_e32 v2, v2, v3
	v_add_f32_e32 v17, 0, v2
	v_sub_f32_e32 v2, v134, v16
	v_sub_f32_e32 v3, v135, v16
	v_sub_f32_e32 v8, v8, v16
	v_sub_f32_e32 v9, v9, v16
	v_exp_f32_e32 v2, v2
	v_exp_f32_e32 v3, v3
	v_exp_f32_e32 v8, v8
	v_exp_f32_e32 v9, v9
	v_sub_f32_e32 v10, v10, v16
	v_sub_f32_e32 v11, v11, v16
	v_sub_f32_e32 v14, v14, v16
	v_sub_f32_e32 v15, v15, v16
	v_add_f32_e32 v138, v4, v5
	v_add_f32_e32 v139, v12, v13
	v_exp_f32_e32 v10, v10
	v_exp_f32_e32 v11, v11
	v_exp_f32_e32 v14, v14
	v_exp_f32_e32 v15, v15
	v_add_f32_e32 v134, v138, v139
	v_add_f32_e32 v17, v134, v17
	v_add_f32_e32 v134, v2, v3
	v_add_f32_e32 v135, v8, v9
	v_add_f32_e32 v16, v134, v135
	v_add_f32_e32 v16, v16, v17
	v_add_f32_e32 v17, v10, v11
	v_add_f32_e32 v134, v14, v15
	v_add_f32_e32 v17, v17, v134
	v_add_f32_e32 v16, v17, v16
	v_mov_b32_e32 v17, v16
	s_nop 1
	v_permlane16_swap_b32_e32 v16, v17
	s_waitcnt lgkmcnt(0)
	v_add_f32_e32 v16, v16, v17
	v_mov_b32_e32 v17, v16
	s_nop 1
	v_permlane32_swap_b32_e32 v16, v17
	s_and_saveexec_b64 s[0:1], s[6:7]
	s_cbranch_execz .LBB0_1751
	s_waitcnt lgkmcnt(0)
	v_add_f32_e32 v16, v16, v17
	ds_write_b32 v210, v16 offset:2816
